# grid barrier: the XCD leader issues the relay add for its followers before its own buffer_inv and no longer waits for its fire-and-forget adds first
# baseline (speedup 1.0000x reference)
.LBB0_57:
	s_or_b64 exec, exec, s[16:17]
	s_mov_b64 s[16:17], exec
	v_mbcnt_lo_u32_b32 v2, s16, 0
	v_mbcnt_hi_u32_b32 v2, s17, v2
	v_cmp_eq_u32_e32 vcc, 0, v2
	s_and_saveexec_b64 s[18:19], vcc
	s_cbranch_execz .LBB0_59
	s_bcnt1_i32_b64 s2, s[16:17]
	v_readlane_b32 s16, v254, 9
	v_mov_b32_e32 v2, s2
	v_readlane_b32 s17, v254, 10
	s_nop 4
	global_atomic_add v196, v2, s[16:17]
.LBB0_59:
	s_or_b64 exec, exec, s[18:19]
	buffer_inv sc1
	s_waitcnt vmcnt(0)
